# as v6 plus in-proj E.pre split: rstd loads issued before the align barrier, completed after the epilogue stores with counted vmcnt(16)
# speedup vs baseline: 1.0029x; 1.0029x over previous
; #define PG8_STAGE(bufoff, gbase, voff) do { _Pragma("unroll") for (int _i = 0; _i < 2; ++_i) \
;         __builtin_amdgcn_global_load_lds((const unsigned*)((const char*)(gbase) + (voff)[_i]), (LAS unsigned*)(lds + (bufoff) + ldsw + _i * 8192), 16, 0, 0); } while (0)
; #define PG8_LDA(dst, b, h) do { _Pragma("unroll") for (int m = 0; m < 4; ++m) _Pragma("unroll") for (int k = 0; k < 2; ++k) dst[m][k] = *(const LAS bf16x8*)(lds + PG8_SA(b, h) + aoff + m * 2048 + k * 1024); } while (0)
; #define PG8_MMA(ai, bj, At, Bt) do { __builtin_amdgcn_s_setprio(1); _Pragma("unroll") for (int m = 0; m < 4; ++m) _Pragma("unroll") for (int n = 0; n < 2; ++n) _Pragma("unroll") for (int k = 0; k < 2; ++k) \
;         acc[ai][bj][m][n] = __builtin_amdgcn_mfma_f32_16x16x32_bf16(Bt[n][k], At[m][k], acc[ai][bj][m][n], 0, 0, 0); __builtin_amdgcn_s_setprio(0); } while (0)
; #define PG8_WAIT_V(n) asm volatile("s_waitcnt vmcnt(" #n ")" ::: "memory")
; #define PG8_WAIT_L(n) asm volatile("s_waitcnt lgkmcnt(" #n ")" ::: "memory")
; #define PG8_BAR __builtin_amdgcn_s_barrier()
; #define PG8_SCHED __builtin_amdgcn_sched_barrier(0)
; template <class Epi, bool ALIGN_EPI = true, class Sched = StaticOrder>
; __device__ __forceinline__ void gemm_phase(LAS unsigned char* lds, const Gemm g, const Sched& S, const Epi& E) {
;     ...
;             PG8_WAIT_V(8); PG8_WAIT_L(0); PG8_BAR; PG8_MMA(0, 0, At, B0); PG8_MMA(0, 1, At, B1); PG8_BAR; PG8_SCHED;
;             PG8_LDA(At, 0, 1); PG8_STAGE(PG8_SB(0, 0), b2, voffB); PG8_STAGE(PG8_SB(0, 1), b2 + hstepB, voffB); PG8_STAGE(PG8_SA(0, 0), a2, voffA);
;             PG8_WAIT_V(8); PG8_WAIT_L(0); PG8_BAR; PG8_MMA(1, 0, At, B0); PG8_MMA(1, 1, At, B1); PG8_BAR; PG8_SCHED;
.Lwj_s0p:
	s_waitcnt lgkmcnt(0)
	s_barrier
	s_setprio 1
	s_waitcnt lgkmcnt(0)
	v_mfma_f32_16x16x32_bf16 v[126:129], v[140:143], v[180:183], v[126:129]
	v_mfma_f32_16x16x32_bf16 v[122:125], v[156:159], v[180:183], v[122:125]
	v_mfma_f32_16x16x32_bf16 v[118:121], v[140:143], v[198:201], v[118:121]
	v_mfma_f32_16x16x32_bf16 v[110:113], v[156:159], v[198:201], v[110:113]
	v_mfma_f32_16x16x32_bf16 v[102:105], v[140:143], v[216:219], v[102:105]
	v_mfma_f32_16x16x32_bf16 v[94:97], v[156:159], v[216:219], v[94:97]
	v_mfma_f32_16x16x32_bf16 v[86:89], v[140:143], v[224:227], v[86:89]
	v_mfma_f32_16x16x32_bf16 v[78:81], v[156:159], v[224:227], v[78:81]
	v_mfma_f32_16x16x32_bf16 v[126:129], v[152:155], v[184:187], v[126:129]
	v_mfma_f32_16x16x32_bf16 v[122:125], v[160:163], v[184:187], v[122:125]
	v_mfma_f32_16x16x32_bf16 v[118:121], v[152:155], v[202:205], v[118:121]
	v_mfma_f32_16x16x32_bf16 v[110:113], v[160:163], v[202:205], v[110:113]
	v_mfma_f32_16x16x32_bf16 v[102:105], v[152:155], v[220:223], v[102:105]
	v_mfma_f32_16x16x32_bf16 v[94:97], v[160:163], v[220:223], v[94:97]
	v_mfma_f32_16x16x32_bf16 v[86:89], v[152:155], v[234:237], v[86:89]
	v_mfma_f32_16x16x32_bf16 v[78:81], v[160:163], v[234:237], v[78:81]
	s_setprio 0
	s_setprio 1
	v_mfma_f32_16x16x32_bf16 v[114:117], v[164:167], v[180:183], v[114:117]
	v_mfma_f32_16x16x32_bf16 v[106:109], v[172:175], v[180:183], v[106:109]
	v_mfma_f32_16x16x32_bf16 v[98:101], v[164:167], v[198:201], v[98:101]
	v_mfma_f32_16x16x32_bf16 v[90:93], v[172:175], v[198:201], v[90:93]
	v_mfma_f32_16x16x32_bf16 v[82:85], v[164:167], v[216:219], v[82:85]
	v_mfma_f32_16x16x32_bf16 v[74:77], v[172:175], v[216:219], v[74:77]
	v_mfma_f32_16x16x32_bf16 v[70:73], v[164:167], v[224:227], v[70:73]
	v_mfma_f32_16x16x32_bf16 v[66:69], v[172:175], v[224:227], v[66:69]
	v_mfma_f32_16x16x32_bf16 v[114:117], v[168:171], v[184:187], v[114:117]
	v_mfma_f32_16x16x32_bf16 v[106:109], v[176:179], v[184:187], v[106:109]
	v_mfma_f32_16x16x32_bf16 v[98:101], v[168:171], v[202:205], v[98:101]
	v_mfma_f32_16x16x32_bf16 v[90:93], v[176:179], v[202:205], v[90:93]
	v_mfma_f32_16x16x32_bf16 v[82:85], v[168:171], v[220:223], v[82:85]
	v_mfma_f32_16x16x32_bf16 v[74:77], v[176:179], v[220:223], v[74:77]
	v_mfma_f32_16x16x32_bf16 v[70:73], v[168:171], v[234:237], v[70:73]
	v_mfma_f32_16x16x32_bf16 v[66:69], v[176:179], v[234:237], v[66:69]
	s_setprio 0
	s_barrier
	s_add_i32 s46, s46, s19
	v_lshl_add_u64 v[188:189], s[60:61], 0, v[0:1]
	s_mov_b32 m0, s46
	ds_read_b128 v[180:183], v151 offset:16384
	ds_read_b128 v[184:187], v151 offset:17408
	ds_read_b128 v[198:201], v151 offset:18432
	ds_read_b128 v[202:205], v151 offset:19456
	ds_read_b128 v[216:219], v151 offset:20480
	ds_read_b128 v[220:223], v151 offset:21504
	ds_read_b128 v[224:227], v151 offset:22528
	ds_read_b128 v[234:237], v151 offset:23552
	global_load_lds_dwordx4 v[188:189], off
	s_add_i32 m0, s46, 0x2000
	s_add_u32 s46, s60, 0x40000
	v_lshl_add_u64 v[190:191], s[60:61], 0, v[134:135]
	s_addc_u32 s47, s61, 0
	s_add_i32 s48, s48, s19
	global_load_lds_dwordx4 v[190:191], off
	v_lshl_add_u64 v[192:193], s[46:47], 0, v[0:1]
	s_mov_b32 m0, s48
	v_lshl_add_u64 v[194:195], s[36:37], 0, v[132:133]
	global_load_lds_dwordx4 v[192:193], off
	v_lshl_add_u64 v[192:193], s[46:47], 0, v[134:135]
	s_add_i32 m0, s48, 0x2000
	s_nop 0
	global_load_lds_dwordx4 v[192:193], off
	v_lshl_add_u64 v[192:193], s[36:37], 0, v[130:131]
	s_waitcnt vmcnt(6)
	s_waitcnt lgkmcnt(0)
	s_barrier
	s_setprio 1
	s_waitcnt lgkmcnt(0)
	v_mfma_f32_16x16x32_bf16 v[62:65], v[140:143], v[180:183], v[62:65]
	v_mfma_f32_16x16x32_bf16 v[58:61], v[156:159], v[180:183], v[58:61]
	v_mfma_f32_16x16x32_bf16 v[54:57], v[140:143], v[198:201], v[54:57]
	v_mfma_f32_16x16x32_bf16 v[46:49], v[156:159], v[198:201], v[46:49]
	v_mfma_f32_16x16x32_bf16 v[38:41], v[140:143], v[216:219], v[38:41]
	v_mfma_f32_16x16x32_bf16 v[30:33], v[156:159], v[216:219], v[30:33]
	v_mfma_f32_16x16x32_bf16 v[22:25], v[140:143], v[224:227], v[22:25]
	v_mfma_f32_16x16x32_bf16 v[14:17], v[156:159], v[224:227], v[14:17]
	v_mfma_f32_16x16x32_bf16 v[62:65], v[152:155], v[184:187], v[62:65]
	v_mfma_f32_16x16x32_bf16 v[58:61], v[160:163], v[184:187], v[58:61]
	v_mfma_f32_16x16x32_bf16 v[54:57], v[152:155], v[202:205], v[54:57]
	v_mfma_f32_16x16x32_bf16 v[46:49], v[160:163], v[202:205], v[46:49]
	v_mfma_f32_16x16x32_bf16 v[38:41], v[152:155], v[220:223], v[38:41]
	v_mfma_f32_16x16x32_bf16 v[30:33], v[160:163], v[220:223], v[30:33]
	v_mfma_f32_16x16x32_bf16 v[22:25], v[152:155], v[234:237], v[22:25]
	v_mfma_f32_16x16x32_bf16 v[14:17], v[160:163], v[234:237], v[14:17]
	s_setprio 0
	s_setprio 1
	v_mfma_f32_16x16x32_bf16 v[50:53], v[164:167], v[180:183], v[50:53]
	v_mfma_f32_16x16x32_bf16 v[42:45], v[172:175], v[180:183], v[42:45]
	v_mfma_f32_16x16x32_bf16 v[34:37], v[164:167], v[198:201], v[34:37]
	v_mfma_f32_16x16x32_bf16 v[26:29], v[172:175], v[198:201], v[26:29]
	v_mfma_f32_16x16x32_bf16 v[18:21], v[164:167], v[216:219], v[18:21]
	v_mfma_f32_16x16x32_bf16 v[10:13], v[172:175], v[216:219], v[10:13]
	v_mfma_f32_16x16x32_bf16 v[6:9], v[164:167], v[224:227], v[6:9]
	v_mfma_f32_16x16x32_bf16 v[2:5], v[172:175], v[224:227], v[2:5]
	v_mfma_f32_16x16x32_bf16 v[50:53], v[168:171], v[184:187], v[50:53]
	v_mfma_f32_16x16x32_bf16 v[42:45], v[176:179], v[184:187], v[42:45]
	v_mfma_f32_16x16x32_bf16 v[34:37], v[168:171], v[202:205], v[34:37]
	v_mfma_f32_16x16x32_bf16 v[26:29], v[176:179], v[202:205], v[26:29]
	v_mfma_f32_16x16x32_bf16 v[18:21], v[168:171], v[220:223], v[18:21]
	v_mfma_f32_16x16x32_bf16 v[10:13], v[176:179], v[220:223], v[10:13]
	v_mfma_f32_16x16x32_bf16 v[6:9], v[168:171], v[234:237], v[6:9]
	v_mfma_f32_16x16x32_bf16 v[2:5], v[176:179], v[234:237], v[2:5]
	s_setprio 0
	s_barrier
; #define PG8_STAGE(bufoff, gbase, voff) do { _Pragma("unroll") for (int _i = 0; _i < 2; ++_i) \
;         __builtin_amdgcn_global_load_lds((const unsigned*)((const char*)(gbase) + (voff)[_i]), (LAS unsigned*)(lds + (bufoff) + ldsw + _i * 8192), 16, 0, 0); } while (0)
; #define PG8_LDA(dst, b, h) do { _Pragma("unroll") for (int m = 0; m < 4; ++m) _Pragma("unroll") for (int k = 0; k < 2; ++k) dst[m][k] = *(const LAS bf16x8*)(lds + PG8_SA(b, h) + aoff + m * 2048 + k * 1024); } while (0)
; #define PG8_LDB(dst, b, h) do { _Pragma("unroll") for (int n = 0; n < 2; ++n) _Pragma("unroll") for (int k = 0; k < 2; ++k) dst[n][k] = *(const LAS bf16x8*)(lds + PG8_SB(b, h) + boff + n * 2048 + k * 1024); } while (0)
; #define PG8_MMA(ai, bj, At, Bt) do { __builtin_amdgcn_s_setprio(1); _Pragma("unroll") for (int m = 0; m < 4; ++m) _Pragma("unroll") for (int n = 0; n < 2; ++n) _Pragma("unroll") for (int k = 0; k < 2; ++k) \
;         acc[ai][bj][m][n] = __builtin_amdgcn_mfma_f32_16x16x32_bf16(Bt[n][k], At[m][k], acc[ai][bj][m][n], 0, 0, 0); __builtin_amdgcn_s_setprio(0); } while (0)
; #define PG8_WAIT_V(n) asm volatile("s_waitcnt vmcnt(" #n ")" ::: "memory")
; #define PG8_WAIT_L(n) asm volatile("s_waitcnt lgkmcnt(" #n ")" ::: "memory")
; #define PG8_BAR __builtin_amdgcn_s_barrier()
; #define PG8_SCHED __builtin_amdgcn_sched_barrier(0)
; template <class Epi, bool ALIGN_EPI = true, class Sched = StaticOrder>
; __device__ __forceinline__ void gemm_phase(LAS unsigned char* lds, const Gemm g, const Sched& S, const Epi& E) {
;     ...
;             PG8_LDB(B0, 1, 0); PG8_LDB(B1, 1, 1); PG8_SCHED; PG8_LDA(At, 1, 0); PG8_STAGE(PG8_SA(0, 1), a2 + hstepA, voffA);
;             PG8_WAIT_V(8); PG8_WAIT_L(0); PG8_BAR; PG8_MMA(0, 0, At, B0); PG8_MMA(0, 1, At, B1); PG8_BAR; PG8_SCHED;
	s_mov_b32 m0, s11
	s_nop 0
	global_load_lds_dwordx4 v[192:193], off
	s_mov_b32 m0, s25
	s_nop 0
	global_load_lds_dwordx4 v[194:195], off
	s_add_i32 s46, 0, 0x18000
	s_add_i32 s47, 0, 0x1c000
	v_add_u32_e32 v160, s46, v145
	v_add_u32_e32 v176, s47, v145
	ds_read_b128 v[140:143], v160
	ds_read_b128 v[152:155], v160 offset:1024
	ds_read_b128 v[156:159], v160 offset:2048
	ds_read_b128 v[160:163], v160 offset:3072
	ds_read_b128 v[164:167], v176
	ds_read_b128 v[168:171], v176 offset:1024
	ds_read_b128 v[172:175], v176 offset:2048
	ds_read_b128 v[176:179], v176 offset:3072
	s_add_u32 s36, s36, 0x40000
	s_addc_u32 s37, s37, 0
	s_mov_b32 m0, s26
	v_lshl_add_u64 v[196:197], s[36:37], 0, v[130:131]
	ds_read_b128 v[180:183], v151 offset:32768
	ds_read_b128 v[184:187], v151 offset:33792
	ds_read_b128 v[198:201], v151 offset:34816
	ds_read_b128 v[202:205], v151 offset:35840
	ds_read_b128 v[216:219], v151 offset:36864
	ds_read_b128 v[220:223], v151 offset:37888
	ds_read_b128 v[224:227], v151 offset:38912
	ds_read_b128 v[234:237], v151 offset:39936
	global_load_lds_dwordx4 v[196:197], off
	v_lshl_add_u64 v[196:197], s[36:37], 0, v[132:133]
	s_mov_b32 m0, s27
	s_nop 0
	global_load_lds_dwordx4 v[196:197], off
	s_waitcnt vmcnt(8)
	s_waitcnt lgkmcnt(0)
	s_barrier
	s_setprio 1
	s_waitcnt lgkmcnt(0)
	v_mfma_f32_16x16x32_bf16 v[126:129], v[140:143], v[180:183], v[126:129]
	v_mfma_f32_16x16x32_bf16 v[122:125], v[156:159], v[180:183], v[122:125]
	v_mfma_f32_16x16x32_bf16 v[118:121], v[140:143], v[198:201], v[118:121]
	v_mfma_f32_16x16x32_bf16 v[110:113], v[156:159], v[198:201], v[110:113]
	v_mfma_f32_16x16x32_bf16 v[102:105], v[140:143], v[216:219], v[102:105]
	v_mfma_f32_16x16x32_bf16 v[94:97], v[156:159], v[216:219], v[94:97]
	v_mfma_f32_16x16x32_bf16 v[86:89], v[140:143], v[224:227], v[86:89]
	v_mfma_f32_16x16x32_bf16 v[78:81], v[156:159], v[224:227], v[78:81]
	v_mfma_f32_16x16x32_bf16 v[126:129], v[152:155], v[184:187], v[126:129]
	v_mfma_f32_16x16x32_bf16 v[122:125], v[160:163], v[184:187], v[122:125]
	v_mfma_f32_16x16x32_bf16 v[118:121], v[152:155], v[202:205], v[118:121]
	v_mfma_f32_16x16x32_bf16 v[110:113], v[160:163], v[202:205], v[110:113]
	v_mfma_f32_16x16x32_bf16 v[102:105], v[152:155], v[220:223], v[102:105]
	v_mfma_f32_16x16x32_bf16 v[94:97], v[160:163], v[220:223], v[94:97]
	v_mfma_f32_16x16x32_bf16 v[86:89], v[152:155], v[234:237], v[86:89]
	v_mfma_f32_16x16x32_bf16 v[78:81], v[160:163], v[234:237], v[78:81]
	s_setprio 0
	s_setprio 1
	v_mfma_f32_16x16x32_bf16 v[114:117], v[164:167], v[180:183], v[114:117]
	v_mfma_f32_16x16x32_bf16 v[106:109], v[172:175], v[180:183], v[106:109]
	v_mfma_f32_16x16x32_bf16 v[98:101], v[164:167], v[198:201], v[98:101]
	v_mfma_f32_16x16x32_bf16 v[90:93], v[172:175], v[198:201], v[90:93]
	v_mfma_f32_16x16x32_bf16 v[82:85], v[164:167], v[216:219], v[82:85]
	v_mfma_f32_16x16x32_bf16 v[74:77], v[172:175], v[216:219], v[74:77]
	v_mfma_f32_16x16x32_bf16 v[70:73], v[164:167], v[224:227], v[70:73]
	v_mfma_f32_16x16x32_bf16 v[66:69], v[172:175], v[224:227], v[66:69]
	v_mfma_f32_16x16x32_bf16 v[114:117], v[168:171], v[184:187], v[114:117]
	v_mfma_f32_16x16x32_bf16 v[106:109], v[176:179], v[184:187], v[106:109]
	v_mfma_f32_16x16x32_bf16 v[98:101], v[168:171], v[202:205], v[98:101]
	v_mfma_f32_16x16x32_bf16 v[90:93], v[176:179], v[202:205], v[90:93]
	v_mfma_f32_16x16x32_bf16 v[82:85], v[168:171], v[220:223], v[82:85]
	v_mfma_f32_16x16x32_bf16 v[74:77], v[176:179], v[220:223], v[74:77]
	v_mfma_f32_16x16x32_bf16 v[70:73], v[168:171], v[234:237], v[70:73]
	v_mfma_f32_16x16x32_bf16 v[66:69], v[176:179], v[234:237], v[66:69]
	s_setprio 0
	s_barrier
; #define PG8_STAGE(bufoff, gbase, voff) do { _Pragma("unroll") for (int _i = 0; _i < 2; ++_i) \
;         __builtin_amdgcn_global_load_lds((const unsigned*)((const char*)(gbase) + (voff)[_i]), (LAS unsigned*)(lds + (bufoff) + ldsw + _i * 8192), 16, 0, 0); } while (0)
; #define PG8_LDA(dst, b, h) do { _Pragma("unroll") for (int m = 0; m < 4; ++m) _Pragma("unroll") for (int k = 0; k < 2; ++k) dst[m][k] = *(const LAS bf16x8*)(lds + PG8_SA(b, h) + aoff + m * 2048 + k * 1024); } while (0)
; #define PG8_MMA(ai, bj, At, Bt) do { __builtin_amdgcn_s_setprio(1); _Pragma("unroll") for (int m = 0; m < 4; ++m) _Pragma("unroll") for (int n = 0; n < 2; ++n) _Pragma("unroll") for (int k = 0; k < 2; ++k) \
;         acc[ai][bj][m][n] = __builtin_amdgcn_mfma_f32_16x16x32_bf16(Bt[n][k], At[m][k], acc[ai][bj][m][n], 0, 0, 0); __builtin_amdgcn_s_setprio(0); } while (0)
; #define PG8_WAIT_V(n) asm volatile("s_waitcnt vmcnt(" #n ")" ::: "memory")
; #define PG8_WAIT_L(n) asm volatile("s_waitcnt lgkmcnt(" #n ")" ::: "memory")
; #define PG8_BAR __builtin_amdgcn_s_barrier()
; #define PG8_SCHED __builtin_amdgcn_sched_barrier(0)
; template <class Epi, bool ALIGN_EPI = true, class Sched = StaticOrder>
; __device__ __forceinline__ void gemm_phase(LAS unsigned char* lds, const Gemm g, const Sched& S, const Epi& E) {
;     ...
;             PG8_LDA(At, 1, 1); PG8_STAGE(PG8_SB(1, 0), b3, voffB); PG8_STAGE(PG8_SB(1, 1), b3 + hstepB, voffB); PG8_STAGE(PG8_SA(1, 0), a3, voffA);
;             PG8_WAIT_V(8); PG8_WAIT_L(0); PG8_BAR; PG8_MMA(1, 0, At, B0); PG8_MMA(1, 1, At, B1); PG8_BAR; PG8_SCHED;
;         }
;         if constexpr (Epi::HAS_PRE) { if (has_next) E.pre(nxt, (ui + 1) & 1); }
;     __device__ __forceinline__ void pre(const Unit& u, int buf) const {
;         int t = threadIdx.x; asm volatile("" : "+v"(t));
;         if (t < 256) { const f32x4* sp = (const f32x4*)(ssp + (size_t)(u.pm * BM + t) * 16);
;             const f32x4 s4 = (sp[0] + sp[1]) + (sp[2] + sp[3]);
;             stash[buf * 256 + t] = __builtin_amdgcn_rsqf(((s4[0] + s4[1]) + (s4[2] + s4[3])) * (1.f / 1024.f) + EPS); }
	s_add_i32 s36, s46, s19
	v_lshl_add_u64 v[188:189], v[188:189], 0, s[70:71]
	s_mov_b32 m0, s36
	ds_read_b128 v[180:183], v151 offset:49152
	ds_read_b128 v[184:187], v151 offset:50176
	ds_read_b128 v[198:201], v151 offset:51200
	ds_read_b128 v[202:205], v151 offset:52224
	ds_read_b128 v[216:219], v151 offset:53248
	ds_read_b128 v[220:223], v151 offset:54272
	ds_read_b128 v[224:227], v151 offset:55296
	ds_read_b128 v[234:237], v151 offset:56320
	global_load_lds_dwordx4 v[188:189], off
	s_add_i32 m0, s36, 0x2000
	s_add_u32 s36, s60, 0x40080
	v_lshl_add_u64 v[188:189], v[190:191], 0, s[70:71]
	s_addc_u32 s37, s61, 0
	s_add_i32 s46, s47, s19
	global_load_lds_dwordx4 v[188:189], off
	v_lshl_add_u64 v[188:189], s[36:37], 0, v[0:1]
	s_mov_b32 m0, s46
	s_nop 0
	global_load_lds_dwordx4 v[188:189], off
	v_lshl_add_u64 v[188:189], s[36:37], 0, v[134:135]
	s_add_i32 m0, s46, 0x2000
	s_nop 0
	global_load_lds_dwordx4 v[188:189], off
	s_waitcnt vmcnt(6)
	s_waitcnt lgkmcnt(0)
	s_barrier
	s_setprio 1
	s_waitcnt lgkmcnt(0)
	v_mfma_f32_16x16x32_bf16 v[62:65], v[140:143], v[180:183], v[62:65]
	v_mfma_f32_16x16x32_bf16 v[58:61], v[156:159], v[180:183], v[58:61]
	v_mfma_f32_16x16x32_bf16 v[54:57], v[140:143], v[198:201], v[54:57]
	v_mfma_f32_16x16x32_bf16 v[46:49], v[156:159], v[198:201], v[46:49]
	v_mfma_f32_16x16x32_bf16 v[38:41], v[140:143], v[216:219], v[38:41]
	v_mfma_f32_16x16x32_bf16 v[30:33], v[156:159], v[216:219], v[30:33]
	v_mfma_f32_16x16x32_bf16 v[22:25], v[140:143], v[224:227], v[22:25]
	v_mfma_f32_16x16x32_bf16 v[14:17], v[156:159], v[224:227], v[14:17]
	v_mfma_f32_16x16x32_bf16 v[62:65], v[152:155], v[184:187], v[62:65]
	v_mfma_f32_16x16x32_bf16 v[58:61], v[160:163], v[184:187], v[58:61]
	v_mfma_f32_16x16x32_bf16 v[54:57], v[152:155], v[202:205], v[54:57]
	v_mfma_f32_16x16x32_bf16 v[46:49], v[160:163], v[202:205], v[46:49]
	v_mfma_f32_16x16x32_bf16 v[38:41], v[152:155], v[220:223], v[38:41]
	v_mfma_f32_16x16x32_bf16 v[30:33], v[160:163], v[220:223], v[30:33]
	v_mfma_f32_16x16x32_bf16 v[22:25], v[152:155], v[234:237], v[22:25]
	v_mfma_f32_16x16x32_bf16 v[14:17], v[160:163], v[234:237], v[14:17]
	s_setprio 0
	s_setprio 1
	v_mfma_f32_16x16x32_bf16 v[50:53], v[164:167], v[180:183], v[50:53]
	v_mfma_f32_16x16x32_bf16 v[42:45], v[172:175], v[180:183], v[42:45]
	v_mfma_f32_16x16x32_bf16 v[34:37], v[164:167], v[198:201], v[34:37]
	v_mfma_f32_16x16x32_bf16 v[26:29], v[172:175], v[198:201], v[26:29]
	v_mfma_f32_16x16x32_bf16 v[18:21], v[164:167], v[216:219], v[18:21]
	v_mfma_f32_16x16x32_bf16 v[10:13], v[172:175], v[216:219], v[10:13]
	v_mfma_f32_16x16x32_bf16 v[6:9], v[164:167], v[224:227], v[6:9]
	v_mfma_f32_16x16x32_bf16 v[2:5], v[172:175], v[224:227], v[2:5]
	v_mfma_f32_16x16x32_bf16 v[50:53], v[168:171], v[184:187], v[50:53]
	v_mfma_f32_16x16x32_bf16 v[42:45], v[176:179], v[184:187], v[42:45]
	v_mfma_f32_16x16x32_bf16 v[34:37], v[168:171], v[202:205], v[34:37]
	v_mfma_f32_16x16x32_bf16 v[26:29], v[176:179], v[202:205], v[26:29]
	v_mfma_f32_16x16x32_bf16 v[18:21], v[168:171], v[220:223], v[18:21]
	v_mfma_f32_16x16x32_bf16 v[10:13], v[176:179], v[220:223], v[10:13]
	v_mfma_f32_16x16x32_bf16 v[6:9], v[168:171], v[234:237], v[6:9]
	v_mfma_f32_16x16x32_bf16 v[2:5], v[176:179], v[234:237], v[2:5]
	s_setprio 0
	s_barrier
	s_add_i32 s45, s45, 2
	s_add_u32 s58, s58, 0x100
	s_addc_u32 s59, s59, 0
	s_add_u32 s43, s43, 0x100
	s_addc_u32 s44, s44, 0
	s_cmp_gt_u32 s45, 13
	s_cbranch_scc0 .LBB0_374
	s_mov_b32 s100, 0
	s_and_b64 vcc, exec, s[0:1]
	s_cbranch_vccz .LBB0_379
	v_mov_b32_e32 v140, v208
	s_nop 0
	v_cmp_gt_i32_e32 vcc, s78, v140
	s_and_saveexec_b64 s[12:13], vcc
	s_cbranch_execz .LBB0_378
	v_lshl_add_u32 v142, s8, 8, v140
	v_ashrrev_i32_e32 v143, 31, v142
	v_lshlrev_b64 v[142:143], 6, v[142:143]
	v_lshl_add_u64 v[142:143], s[82:83], 0, v[142:143]
	global_load_dwordx4 v[160:163], v[142:143], off
	global_load_dwordx4 v[164:167], v[142:143], off offset:16
	global_load_dwordx4 v[168:171], v[142:143], off offset:32
	global_load_dwordx4 v[172:175], v[142:143], off offset:48
	s_lshl_b32 s7, s41, 10
	s_and_b32 s7, s7, 0x400
	s_add_i32 s7, s7, 0
	v_lshl_add_u32 v140, v140, 2, s7
	v_add_u32_e32 v176, 0x20600, v140
	s_mov_b32 s100, 1

; __device__ __forceinline__ unsigned pk2(float lo, float hi) { f32x2 v = {lo, hi}; bf16x2_t b = __builtin_convertvector(v, bf16x2_t); return __builtin_bit_cast(unsigned, b); }
;     __device__ __forceinline__ void operator()(const f32x4 (&acc)[2][2][4][2], const Unit& u, int wr, int wc, int fr, int fq, int buf) const {
;         const int rl0 = wr * 64 + fr, col0 = u.pn * BM + wc * 32 + 8 * fq;
; #pragma unroll
;         for (int ai = 0; ai < 2; ++ai)
; #pragma unroll
;             for (int m = 0; m < 4; ++m) {
;                 const int rl = rl0 + ai * HALF + m * 16;
;                 const float rs = stash[buf * 256 + rl];
;                 bf16_t* rowp = O + (size_t)(u.pm * BM + rl) * LDP + col0;
; #pragma unroll
;                 for (int bj = 0; bj < 2; ++bj) { const f32x4 v0 = acc[ai][bj][m][0] * rs, v1 = acc[ai][bj][m][1] * rs;
;                     u32x4 w; w.x = pk2(v0[0], v0[1]); w.y = pk2(v0[2], v0[3]); w.z = pk2(v1[0], v1[1]); w.w = pk2(v1[2], v1[3]);
;                     *(u32x4*)(rowp + bj * HALF) = w; }
;             }
;     }
.LBB0_381:
	s_lshl_b32 s7, s42, 10
	s_and_b32 s7, s7, 0x400
	v_add_u32_e32 v158, s7, v150
	ds_read2_b32 v[152:153], v158 offset1:16
	v_lshl_or_b32 v142, s54, 8, v149
	s_lshl_b32 s9, s10, 8
	v_ashrrev_i32_e32 v143, 31, v142
	v_add_u32_e32 v159, s9, v144
	v_mov_b64_e32 v[140:141], s[94:95]
	v_mad_i64_i32 v[154:155], s[12:13], v159, s28, v[140:141]
	v_lshlrev_b64 v[142:143], 1, v[142:143]
	s_waitcnt lgkmcnt(0)
	v_pk_mul_f32 v[128:129], v[128:129], v[152:153] op_sel_hi:[1,0]
	v_pk_mul_f32 v[126:127], v[126:127], v[152:153] op_sel_hi:[1,0]
	v_pk_mul_f32 v[156:157], v[124:125], v[152:153] op_sel_hi:[1,0]
	v_pk_mul_f32 v[124:125], v[122:123], v[152:153] op_sel_hi:[1,0]
	v_lshl_add_u64 v[154:155], v[154:155], 0, v[142:143]
	v_cvt_pk_bf16_f32 v122, v126, v127
	v_cvt_pk_bf16_f32 v123, v128, v129
	v_cvt_pk_bf16_f32 v124, v124, v125
	v_cvt_pk_bf16_f32 v125, v156, v157
	global_store_dwordx4 v[154:155], v[122:125], off
	v_pk_mul_f32 v[116:117], v[116:117], v[152:153] op_sel_hi:[1,0]
	v_pk_mul_f32 v[114:115], v[114:115], v[152:153] op_sel_hi:[1,0]
	v_pk_mul_f32 v[122:123], v[108:109], v[152:153] op_sel_hi:[1,0]
	v_pk_mul_f32 v[108:109], v[106:107], v[152:153] op_sel_hi:[1,0]
	v_cvt_pk_bf16_f32 v106, v114, v115
	v_cvt_pk_bf16_f32 v107, v116, v117
	v_cvt_pk_bf16_f32 v108, v108, v109
	v_cvt_pk_bf16_f32 v109, v122, v123
	global_store_dwordx4 v[154:155], v[106:109], off offset:256
	v_mov_b32_e32 v116, v153
	v_pk_mul_f32 v[112:113], v[112:113], v[116:117] op_sel_hi:[1,0]
	v_add_u32_e32 v106, s9, v146
	v_mad_i64_i32 v[106:107], s[12:13], v106, s28, v[140:141]
	v_lshl_add_u64 v[114:115], v[106:107], 0, v[142:143]
	v_pk_mul_f32 v[108:109], v[120:121], v[116:117] op_sel_hi:[1,0]
	v_pk_mul_f32 v[106:107], v[118:119], v[116:117] op_sel_hi:[1,0]
	v_pk_mul_f32 v[110:111], v[110:111], v[116:117] op_sel_hi:[1,0]
	v_cvt_pk_bf16_f32 v106, v106, v107
	v_cvt_pk_bf16_f32 v107, v108, v109
	v_cvt_pk_bf16_f32 v108, v110, v111
	v_cvt_pk_bf16_f32 v109, v112, v113
	v_pk_mul_f32 v[98:99], v[98:99], v[116:117] op_sel_hi:[1,0]
	global_store_dwordx4 v[114:115], v[106:109], off
	v_pk_mul_f32 v[100:101], v[100:101], v[116:117] op_sel_hi:[1,0]
	s_andn2_b64 vcc, exec, s[0:1]
	v_pk_mul_f32 v[106:107], v[92:93], v[116:117] op_sel_hi:[1,0]
	v_pk_mul_f32 v[92:93], v[90:91], v[116:117] op_sel_hi:[1,0]
	v_cvt_pk_bf16_f32 v90, v98, v99
	ds_read2_b32 v[98:99], v158 offset0:32 offset1:48
	v_cvt_pk_bf16_f32 v91, v100, v101
	v_cvt_pk_bf16_f32 v92, v92, v93
	v_cvt_pk_bf16_f32 v93, v106, v107
	global_store_dwordx4 v[114:115], v[90:93], off offset:256
	s_waitcnt lgkmcnt(0)
	v_pk_mul_f32 v[96:97], v[96:97], v[98:99] op_sel_hi:[1,0]
	v_pk_mul_f32 v[94:95], v[94:95], v[98:99] op_sel_hi:[1,0]
	v_add_u32_e32 v90, s9, v147
	v_mad_i64_i32 v[90:91], s[12:13], v90, s28, v[140:141]
	v_lshl_add_u64 v[100:101], v[90:91], 0, v[142:143]
	v_pk_mul_f32 v[92:93], v[104:105], v[98:99] op_sel_hi:[1,0]
	v_pk_mul_f32 v[90:91], v[102:103], v[98:99] op_sel_hi:[1,0]
	v_pk_mul_f32 v[84:85], v[84:85], v[98:99] op_sel_hi:[1,0]
	v_cvt_pk_bf16_f32 v90, v90, v91
	v_cvt_pk_bf16_f32 v91, v92, v93
	v_cvt_pk_bf16_f32 v92, v94, v95
	v_cvt_pk_bf16_f32 v93, v96, v97
	global_store_dwordx4 v[100:101], v[90:93], off
	v_pk_mul_f32 v[82:83], v[82:83], v[98:99] op_sel_hi:[1,0]
	s_mov_b64 s[0:1], -1
	v_pk_mul_f32 v[90:91], v[76:77], v[98:99] op_sel_hi:[1,0]
	v_pk_mul_f32 v[76:77], v[74:75], v[98:99] op_sel_hi:[1,0]
	v_cvt_pk_bf16_f32 v74, v82, v83
	v_cvt_pk_bf16_f32 v75, v84, v85
	v_cvt_pk_bf16_f32 v76, v76, v77
	v_cvt_pk_bf16_f32 v77, v90, v91
	global_store_dwordx4 v[100:101], v[74:77], off offset:256
	v_mov_b32_e32 v84, v99
	v_pk_mul_f32 v[80:81], v[80:81], v[84:85] op_sel_hi:[1,0]
	v_add_u32_e32 v74, s9, v148
	v_mad_i64_i32 v[74:75], s[12:13], v74, s28, v[140:141]
	v_lshl_add_u64 v[82:83], v[74:75], 0, v[142:143]
	v_pk_mul_f32 v[76:77], v[88:89], v[84:85] op_sel_hi:[1,0]
	v_pk_mul_f32 v[74:75], v[86:87], v[84:85] op_sel_hi:[1,0]
	v_pk_mul_f32 v[78:79], v[78:79], v[84:85] op_sel_hi:[1,0]
	v_cvt_pk_bf16_f32 v74, v74, v75
	v_cvt_pk_bf16_f32 v75, v76, v77
	v_cvt_pk_bf16_f32 v76, v78, v79
	v_cvt_pk_bf16_f32 v77, v80, v81
	global_store_dwordx4 v[82:83], v[74:77], off
	v_pk_mul_f32 v[72:73], v[72:73], v[84:85] op_sel_hi:[1,0]
	v_pk_mul_f32 v[70:71], v[70:71], v[84:85] op_sel_hi:[1,0]
	v_pk_mul_f32 v[74:75], v[68:69], v[84:85] op_sel_hi:[1,0]
	v_pk_mul_f32 v[68:69], v[66:67], v[84:85] op_sel_hi:[1,0]
	v_cvt_pk_bf16_f32 v66, v70, v71
	v_cvt_pk_bf16_f32 v67, v72, v73
	v_cvt_pk_bf16_f32 v68, v68, v69
	v_cvt_pk_bf16_f32 v69, v74, v75
	global_store_dwordx4 v[82:83], v[66:69], off offset:256
	ds_read2_b32 v[66:67], v158 offset0:128 offset1:144
	s_waitcnt lgkmcnt(0)
; __device__ __forceinline__ unsigned pk2(float lo, float hi) { f32x2 v = {lo, hi}; bf16x2_t b = __builtin_convertvector(v, bf16x2_t); return __builtin_bit_cast(unsigned, b); }
;     __device__ __forceinline__ void pre(const Unit& u, int buf) const {
;         int t = threadIdx.x; asm volatile("" : "+v"(t));
;         if (t < 256) { const f32x4* sp = (const f32x4*)(ssp + (size_t)(u.pm * BM + t) * 16);
;             const f32x4 s4 = (sp[0] + sp[1]) + (sp[2] + sp[3]);
;             stash[buf * 256 + t] = __builtin_amdgcn_rsqf(((s4[0] + s4[1]) + (s4[2] + s4[3])) * (1.f / 1024.f) + EPS); }
;     __device__ __forceinline__ void operator()(const f32x4 (&acc)[2][2][4][2], const Unit& u, int wr, int wc, int fr, int fq, int buf) const {
;     ...
;                 const float rs = stash[buf * 256 + rl];
;                 bf16_t* rowp = O + (size_t)(u.pm * BM + rl) * LDP + col0;
; #pragma unroll
;                 for (int bj = 0; bj < 2; ++bj) { const f32x4 v0 = acc[ai][bj][m][0] * rs, v1 = acc[ai][bj][m][1] * rs;
;                     u32x4 w; w.x = pk2(v0[0], v0[1]); w.y = pk2(v0[2], v0[3]); w.z = pk2(v1[0], v1[1]); w.w = pk2(v1[2], v1[3]);
;                     *(u32x4*)(rowp + bj * HALF) = w; }
;             }
;     }
	v_pk_mul_f32 v[64:65], v[64:65], v[66:67] op_sel_hi:[1,0]
	v_add_u32_e32 v68, 0x80, v159
	v_mad_i64_i32 v[68:69], s[12:13], v68, s28, v[140:141]
	v_pk_mul_f32 v[62:63], v[62:63], v[66:67] op_sel_hi:[1,0]
	v_pk_mul_f32 v[70:71], v[60:61], v[66:67] op_sel_hi:[1,0]
	v_pk_mul_f32 v[60:61], v[58:59], v[66:67] op_sel_hi:[1,0]
	v_lshl_add_u64 v[68:69], v[68:69], 0, v[142:143]
	v_cvt_pk_bf16_f32 v58, v62, v63
	v_cvt_pk_bf16_f32 v59, v64, v65
	v_cvt_pk_bf16_f32 v60, v60, v61
	v_cvt_pk_bf16_f32 v61, v70, v71
	global_store_dwordx4 v[68:69], v[58:61], off
	v_pk_mul_f32 v[52:53], v[52:53], v[66:67] op_sel_hi:[1,0]
	v_pk_mul_f32 v[50:51], v[50:51], v[66:67] op_sel_hi:[1,0]
	v_pk_mul_f32 v[58:59], v[44:45], v[66:67] op_sel_hi:[1,0]
	v_pk_mul_f32 v[44:45], v[42:43], v[66:67] op_sel_hi:[1,0]
	v_cvt_pk_bf16_f32 v42, v50, v51
	v_cvt_pk_bf16_f32 v43, v52, v53
	v_cvt_pk_bf16_f32 v44, v44, v45
	v_cvt_pk_bf16_f32 v45, v58, v59
	global_store_dwordx4 v[68:69], v[42:45], off offset:256
	v_mov_b32_e32 v52, v67
	v_pk_mul_f32 v[48:49], v[48:49], v[52:53] op_sel_hi:[1,0]
	v_add_u32_e32 v42, 0x90, v159
	v_mad_i64_i32 v[42:43], s[12:13], v42, s28, v[140:141]
	v_lshl_add_u64 v[50:51], v[42:43], 0, v[142:143]
	v_pk_mul_f32 v[44:45], v[56:57], v[52:53] op_sel_hi:[1,0]
	v_pk_mul_f32 v[42:43], v[54:55], v[52:53] op_sel_hi:[1,0]
	v_pk_mul_f32 v[46:47], v[46:47], v[52:53] op_sel_hi:[1,0]
	v_cvt_pk_bf16_f32 v42, v42, v43
	v_cvt_pk_bf16_f32 v43, v44, v45
	v_cvt_pk_bf16_f32 v44, v46, v47
	v_cvt_pk_bf16_f32 v45, v48, v49
	v_pk_mul_f32 v[34:35], v[34:35], v[52:53] op_sel_hi:[1,0]
	global_store_dwordx4 v[50:51], v[42:45], off
	v_pk_mul_f32 v[36:37], v[36:37], v[52:53] op_sel_hi:[1,0]
	s_nop 0
	v_pk_mul_f32 v[42:43], v[28:29], v[52:53] op_sel_hi:[1,0]
	v_pk_mul_f32 v[28:29], v[26:27], v[52:53] op_sel_hi:[1,0]
	v_cvt_pk_bf16_f32 v26, v34, v35
	ds_read2_b32 v[34:35], v158 offset0:160 offset1:176
	v_cvt_pk_bf16_f32 v27, v36, v37
	v_cvt_pk_bf16_f32 v28, v28, v29
	v_cvt_pk_bf16_f32 v29, v42, v43
	global_store_dwordx4 v[50:51], v[26:29], off offset:256
	s_waitcnt lgkmcnt(0)
	v_pk_mul_f32 v[32:33], v[32:33], v[34:35] op_sel_hi:[1,0]
	v_pk_mul_f32 v[30:31], v[30:31], v[34:35] op_sel_hi:[1,0]
	v_add_u32_e32 v26, 0xa0, v159
	v_mad_i64_i32 v[26:27], s[12:13], v26, s28, v[140:141]
	v_lshl_add_u64 v[36:37], v[26:27], 0, v[142:143]
	v_pk_mul_f32 v[28:29], v[40:41], v[34:35] op_sel_hi:[1,0]
	v_pk_mul_f32 v[26:27], v[38:39], v[34:35] op_sel_hi:[1,0]
	v_pk_mul_f32 v[20:21], v[20:21], v[34:35] op_sel_hi:[1,0]
	v_cvt_pk_bf16_f32 v26, v26, v27
	v_cvt_pk_bf16_f32 v27, v28, v29
	v_cvt_pk_bf16_f32 v28, v30, v31
	v_cvt_pk_bf16_f32 v29, v32, v33
	global_store_dwordx4 v[36:37], v[26:29], off
	v_pk_mul_f32 v[18:19], v[18:19], v[34:35] op_sel_hi:[1,0]
	s_nop 0
	v_pk_mul_f32 v[26:27], v[12:13], v[34:35] op_sel_hi:[1,0]
	v_pk_mul_f32 v[12:13], v[10:11], v[34:35] op_sel_hi:[1,0]
	v_cvt_pk_bf16_f32 v10, v18, v19
	v_cvt_pk_bf16_f32 v11, v20, v21
	v_cvt_pk_bf16_f32 v12, v12, v13
	v_cvt_pk_bf16_f32 v13, v26, v27
	global_store_dwordx4 v[36:37], v[10:13], off offset:256
	v_mov_b32_e32 v20, v35
	v_pk_mul_f32 v[16:17], v[16:17], v[20:21] op_sel_hi:[1,0]
	v_add_u32_e32 v10, 0xb0, v159
	v_mad_i64_i32 v[10:11], s[12:13], v10, s28, v[140:141]
	v_lshl_add_u64 v[18:19], v[10:11], 0, v[142:143]
	v_pk_mul_f32 v[12:13], v[24:25], v[20:21] op_sel_hi:[1,0]
	v_pk_mul_f32 v[10:11], v[22:23], v[20:21] op_sel_hi:[1,0]
	v_pk_mul_f32 v[14:15], v[14:15], v[20:21] op_sel_hi:[1,0]
	v_cvt_pk_bf16_f32 v10, v10, v11
	v_cvt_pk_bf16_f32 v11, v12, v13
	v_cvt_pk_bf16_f32 v12, v14, v15
	v_cvt_pk_bf16_f32 v13, v16, v17
	global_store_dwordx4 v[18:19], v[10:13], off
	v_pk_mul_f32 v[8:9], v[8:9], v[20:21] op_sel_hi:[1,0]
	v_pk_mul_f32 v[6:7], v[6:7], v[20:21] op_sel_hi:[1,0]
	v_pk_mul_f32 v[10:11], v[4:5], v[20:21] op_sel_hi:[1,0]
	v_pk_mul_f32 v[4:5], v[2:3], v[20:21] op_sel_hi:[1,0]
	v_cvt_pk_bf16_f32 v2, v6, v7
	v_cvt_pk_bf16_f32 v3, v8, v9
	v_cvt_pk_bf16_f32 v4, v4, v5
	v_cvt_pk_bf16_f32 v5, v10, v11
	global_store_dwordx4 v[18:19], v[2:5], off offset:256
	s_cmp_eq_u32 s100, 1
	s_cbranch_scc0 .Lpre_skip
	s_waitcnt vmcnt(16)
	v_add_f32_e32 v177, v160, v164
	v_add_f32_e32 v178, v161, v165
	v_add_f32_e32 v179, v162, v166
	v_add_f32_e32 v180, v163, v167
	v_add_f32_e32 v181, v168, v172
	v_add_f32_e32 v182, v169, v173
	v_add_f32_e32 v183, v170, v174
	v_add_f32_e32 v184, v171, v175
	v_add_f32_e32 v177, v177, v181
	v_add_f32_e32 v178, v178, v182
	v_add_f32_e32 v179, v179, v183
	v_add_f32_e32 v180, v180, v184
	v_add_f32_e32 v177, v178, v177
	v_add_f32_e32 v179, v179, v180
	v_add_f32_e32 v177, v177, v179
	v_fmamk_f32 v177, v177, 0x3a800000, v209
	v_rsq_f32_e32 v177, v177
	s_nop 0
	ds_write_b32 v176, v177
.Lpre_skip:
	s_cbranch_vccnz .LBB0_370
	s_andn2_b64 vcc, exec, s[2:3]
	s_cbranch_vccnz .LBB0_369
	s_barrier
	s_branch .LBB0_369
